# attention: + leading half prefetches next step's V(B=0) fragments before its tile barrier
# baseline (speedup 1.0000x reference)
; #define ABAR() asm volatile("s_waitcnt lgkmcnt(0)\n\ts_barrier" ::: "memory")
; __device__ __forceinline__ void attn_unit(int h, int qb_, const Tensors& T, char* lds, LASP unsigned char* ldsl, int tid_in) {
;     ...
;   const int vb0 = (int)(uintptr_t)lds + SHM_K + 128 * g + 32 * (c16 >> 2) + 8 * (c16 & 3);
;   const int kx = (c16 >> 1) & 7, ko0 = c16 * 128 + ((g ^ kx) << 4), ko1 = c16 * 128 + (((4 + g) ^ kx) << 4);
;   const size_t TILE_B = (size_t)KVBLK * PITCH * 2;
;   unsigned op[2][8][2];
; #pragma unroll
;   for (int qb = 0; qb < 2; ++qb)
; #pragma unroll
;     for (int db = 0; db < 8; ++db) { op[qb][db][0] = 0u; op[qb][db][1] = 0u; }
;   {
;     const char* Kt = (const char*)(T.K + h * 128); const char* Vt = (const char*)(T.V + h * 128);
;     const char* Qw = (const char*)T.Q + (size_t)(unsigned)(((q0 + wid * QBLK + c16) * PITCH + h * 128 + g * 8) * 2);
;     bf16x8 qr[2][2];
; #pragma unroll
;     for (int qb = 0; qb < 2; ++qb)
; #pragma unroll
;       for (int ks = 0; ks < 2; ++ks) qr[qb][ks] = *reinterpret_cast<const bf16x8*>(Qw + qb * (16 * PITCH * 2) + ks * 64);
;     float l0 = 0.f, l1 = 0.f; f32x4a o[2][8];
; #pragma unroll
;     for (int qb = 0; qb < 2; ++qb)
; #pragma unroll
;       for (int db = 0; db < 8; ++db) o[qb][db] = (f32x4a){0.f, 0.f, 0.f, 0.f};
;     ...
;     const int hf = wid >> 2; constexpr int dist = 4;
;     f32x4a s[4][2]; bf16x8 pa[2][2];
;     DMA_TILE(0, 0); DMA_TILE(1, 1); DMA_TILE(2, 2); DMA_TILE(3, 3);
;     asm volatile("s_waitcnt vmcnt(6)" ::: "memory");
;     __syncthreads();
;     VSet va, vb_;
;     if (hf) ABAR();
;     qkt2(s, lds, ko0, ko1, qr);
;     if (!hf) ABAR();
;     int sgv = 0, sgd = dist;
.LBB0_567:
	s_and_b32 s4, s4, 0x3fffffc0
	s_lshl_b32 s4, s4, 2
	s_add_i32 s39, s4, 0
	s_add_i32 s39, s39, 0x24000
	s_mov_b64 s[4:5], 0x80c0
	v_lshlrev_b32_e32 v0, 3, v0
	v_lshlrev_b32_e32 v2, 7, v3
	v_lshl_add_u64 v[152:153], v[148:149], 0, s[4:5]
	s_movk_i32 s4, 0x60
	s_cmp_lg_u32 0, -1
	v_and_or_b32 v0, v0, s4, v2
	s_cselect_b32 s4, 0, 0
	v_and_b32_e32 v1, 24, v1
	s_addk_i32 s4, 0x2000
	v_add3_u32 v232, v1, s4, v0
	v_mov_b32_e32 v0, 0
	v_mov_b32_e32 v145, v177
	v_mov_b32_e32 v147, v177
	v_lshl_add_u64 v[150:151], v[148:149], 0, s[84:85]
	s_mov_b32 s42, 4
	v_mov_b32_e32 v203, 0
	s_mov_b32 s43, 0
	s_mov_b32 s44, 0
	v_mov_b32_e32 v217, 0
	v_mov_b32_e32 v202, 0
	v_mov_b32_e32 v216, 0
	v_mov_b32_e32 v201, 0
	v_mov_b32_e32 v215, 0
	v_mov_b32_e32 v200, 0
	v_mov_b32_e32 v213, 0
	v_mov_b32_e32 v199, 0
	v_mov_b32_e32 v211, 0
	v_mov_b32_e32 v198, 0
	v_mov_b32_e32 v209, 0
	v_mov_b32_e32 v197, 0
	v_mov_b32_e32 v207, 0
	v_mov_b32_e32 v196, 0
	v_mov_b32_e32 v204, 0
	v_mov_b32_e32 v222, 0
	v_mov_b32_e32 v237, 0
	v_mov_b32_e32 v220, 0
	v_mov_b32_e32 v236, 0
	v_mov_b32_e32 v219, 0
	v_mov_b32_e32 v235, 0
	v_mov_b32_e32 v218, 0
	v_mov_b32_e32 v234, 0
	v_mov_b32_e32 v214, 0
	v_mov_b32_e32 v233, 0
	v_mov_b32_e32 v212, 0
	v_mov_b32_e32 v225, 0
	v_mov_b32_e32 v210, 0
	v_mov_b32_e32 v224, 0
	v_mov_b32_e32 v208, 0
	v_mov_b32_e32 v223, 0
	v_mov_b32_e32 v1, v0
	v_mov_b32_e32 v2, v0
	v_mov_b32_e32 v3, v0
	v_mov_b32_e32 v20, v0
	v_mov_b32_e32 v21, v0
	v_mov_b32_e32 v22, v0
	v_mov_b32_e32 v23, v0
	v_mov_b32_e32 v24, v0
	v_mov_b32_e32 v25, v0
	v_mov_b32_e32 v26, v0
	v_mov_b32_e32 v27, v0
	v_mov_b32_e32 v28, v0
	v_mov_b32_e32 v29, v0
	v_mov_b32_e32 v30, v0
	v_mov_b32_e32 v31, v0
	v_mov_b32_e32 v32, v0
	v_mov_b32_e32 v33, v0
	v_mov_b32_e32 v34, v0
	v_mov_b32_e32 v35, v0
	v_mov_b32_e32 v36, v0
	v_mov_b32_e32 v37, v0
	v_mov_b32_e32 v38, v0
	v_mov_b32_e32 v39, v0
	v_mov_b32_e32 v40, v0
	v_mov_b32_e32 v41, v0
	v_mov_b32_e32 v42, v0
	v_mov_b32_e32 v43, v0
	v_mov_b32_e32 v44, v0
	v_mov_b32_e32 v45, v0
	v_mov_b32_e32 v46, v0
	v_mov_b32_e32 v47, v0
	v_mov_b32_e32 v48, v0
	v_mov_b32_e32 v49, v0
	v_mov_b32_e32 v50, v0
	v_mov_b32_e32 v51, v0
	v_mov_b32_e32 v52, v0
	v_mov_b32_e32 v53, v0
	v_mov_b32_e32 v54, v0
	v_mov_b32_e32 v55, v0
	v_mov_b32_e32 v72, v0
	v_mov_b32_e32 v73, v0
	v_mov_b32_e32 v74, v0
	v_mov_b32_e32 v75, v0
	v_mov_b32_e32 v76, v0
	v_mov_b32_e32 v77, v0
	v_mov_b32_e32 v78, v0
	v_mov_b32_e32 v79, v0
	v_mov_b32_e32 v84, v0
	v_mov_b32_e32 v85, v0
	v_mov_b32_e32 v86, v0
	v_mov_b32_e32 v87, v0
	v_mov_b32_e32 v100, v0
	v_mov_b32_e32 v101, v0
	v_mov_b32_e32 v102, v0
	v_mov_b32_e32 v103, v0
	v_mov_b32_e32 v104, v0
	v_mov_b32_e32 v105, v0
	v_mov_b32_e32 v106, v0
	v_mov_b32_e32 v107, v0
	v_mov_b32_e32 v108, v0
	v_mov_b32_e32 v109, v0
	v_mov_b32_e32 v110, v0
	v_mov_b32_e32 v111, v0
	v_mov_b32_e32 v154, v0
	v_mov_b32_e32 v155, v0
	s_and_b64 vcc, exec, s[6:7]
	s_cbranch_vccnz .Lattn_nopre
	s_mul_i32 s4, s43, 0x6000
	v_add_u32_e32 v238, s4, v232
	ds_read_b64_tr_b16 v[136:137], v238 offset:0
	ds_read_b64_tr_b16 v[138:139], v238 offset:0x200
	ds_read_b64_tr_b16 v[128:129], v238 offset:0x400
	ds_read_b64_tr_b16 v[130:131], v238 offset:0x600
	ds_read_b64_tr_b16 v[140:141], v238 offset:0x800
	ds_read_b64_tr_b16 v[142:143], v238 offset:0xa00
	ds_read_b64_tr_b16 v[132:133], v238 offset:0xc00
	ds_read_b64_tr_b16 v[134:135], v238 offset:0xe00
.Lattn_nopre:
	s_branch .LBB0_569
.LBB0_568:
	s_add_i32 s44, s44, 1
	s_add_i32 s4, s42, 1
	s_cmp_lg_u32 s42, 5
	s_cselect_b32 s42, s4, 0
	s_cmpk_eq_i32 s44, 0x100
	s_cbranch_scc1 .LBB0_582

; #define SBAR() __builtin_amdgcn_sched_barrier(0)
; #define LWAIT() do { asm volatile("s_waitcnt lgkmcnt(0)" ::: "memory"); SBAR(); } while (0)
; __device__ __forceinline__ void attn_unit(int h, int qb_, const Tensors& T, char* lds, LASP unsigned char* ldsl, int tid_in) {
;     ...
;       { const int vbt = vb0 + sgv * STGB; const int sgk = sgv == NSTG - 1 ? 0 : sgv + 1; __builtin_amdgcn_s_setprio(1);
;         vread<0>(va, vbt); SBAR();
;         if (t + 1 < 2 * NT) qkt2(s, lds + sgk * STGB, ko0, ko1, qr);
;         LWAIT(); vread<1>(vb_, vbt); SBAR(); pvmm<0>(o, va, pa); SBAR();
.LBB0_573:
	s_add_i32 s4, s43, 1
	s_cmp_lg_u32 s43, 5
	s_cselect_b32 s43, s4, 0
	s_mul_i32 s4, s43, 0x6000
	s_add_i32 s4, s4, 0
	v_add_u32_e32 v178, s4, v205
	v_add_u32_e32 v179, s4, v206
	ds_read_b128 v[56:59], v178
	ds_read_b128 v[60:63], v178 offset:2048
	ds_read_b128 v[64:67], v179
	ds_read_b128 v[68:71], v179 offset:2048

; #define SBAR() __builtin_amdgcn_sched_barrier(0)
; #define ABAR() asm volatile("s_waitcnt lgkmcnt(0)\n\ts_barrier" ::: "memory")
; __device__ __forceinline__ void attn_unit(int h, int qb_, const Tensors& T, char* lds, LASP unsigned char* ldsl, int tid_in) {
;     ...
;       { const int vbt = vb0 + sgv * STGB; const int sgk = sgv == NSTG - 1 ? 0 : sgv + 1; __builtin_amdgcn_s_setprio(1);
;         vread<0>(va, vbt); SBAR();
;     ...
;       if (!hf) { asm volatile("s_waitcnt vmcnt(6)" ::: "memory"); ABAR(); }
.LBB0_580:
	s_and_b64 vcc, exec, s[6:7]
	s_cbranch_vccnz .LBB0_568
	s_mul_i32 s4, s43, 0x6000
	v_add_u32_e32 v238, s4, v232
	ds_read_b64_tr_b16 v[136:137], v238 offset:0
	ds_read_b64_tr_b16 v[138:139], v238 offset:0x200
	ds_read_b64_tr_b16 v[128:129], v238 offset:0x400
	ds_read_b64_tr_b16 v[130:131], v238 offset:0x600
	ds_read_b64_tr_b16 v[140:141], v238 offset:0x800
	ds_read_b64_tr_b16 v[142:143], v238 offset:0xa00
	ds_read_b64_tr_b16 v[132:133], v238 offset:0xc00
	ds_read_b64_tr_b16 v[134:135], v238 offset:0xe00
	s_waitcnt vmcnt(6)
	s_waitcnt lgkmcnt(0)
	s_barrier
	s_branch .LBB0_568
